# P6 second-tile rotation by four column units instead of one (pairs each heavy epilogue kind with a light one)
# speedup vs baseline: 1.0047x; 1.0047x over previous
.LBB0_635:
	s_add_i32 s21, s21, 1
	v_readlane_b32 s2, v255, 4
	s_mul_i32 s6, s21, s2
	s_mul_hi_u32 s7, s21, s33
	s_add_i32 s7, s7, s6
	s_mul_i32 s6, s21, s33
	s_add_u32 s60, s6, s80
	v_readlane_b32 s2, v255, 5
	s_addc_u32 s61, s7, s2
	s_cmp_eq_u32 s21, 1
	s_cbranch_scc0 .Lp6rot_skip
	s_add_i32 s60, s80, 128
	s_and_b32 s60, s60, 0xff
	s_addk_i32 s60, 0x100
	s_mov_b32 s61, 0
